# cmp_fused_unit: page-table lookups fetched together; A-gather prefetched two K-steps ahead (second register set, loop unrolled x2, vmcnt(8))
# baseline (speedup 1.0000x reference)
.LBB0_1591:
	v_mov_b32_e32 v180, v0
	s_mov_b64 s[6:7], -1
	v_readfirstlane_b32 s22, v180
	s_ashr_i32 s10, s22, 6
	v_and_b32_e32 v182, 63, v180
	s_cmp_lg_u32 s5, s33
	s_cbranch_scc0 .LBB0_1597
	s_waitcnt lgkmcnt(0)
	v_mov_b64_e32 v[2:3], s[0:1]
	s_load_dwordx2 s[98:99], s[0:1], 0x40
	s_waitcnt vmcnt(0) lgkmcnt(0)
	v_mov_b32_e32 v4, s98
	v_mov_b32_e32 v5, s99
	s_load_dwordx2 s[98:99], s[0:1], 0x20
	s_waitcnt vmcnt(0) lgkmcnt(0)
	v_mov_b32_e32 v8, s98
	v_mov_b32_e32 v9, s99
	v_ashrrev_i32_e32 v41, 5, v180
	v_lshlrev_b32_e32 v2, 14, v41
	v_and_b32_e32 v178, 0x1c000, v2
	s_mov_b32 s83, s57
	v_lshlrev_b32_e32 v40, 4, v180
	v_and_b32_e32 v6, 0xf0, v40
	v_mov_b32_e32 v7, v179
	s_lshl_b32 s5, s10, 5
	s_and_b32 s6, s5, 0xffffffc0
	s_lshl_b32 s5, s10, 7
	v_and_b32_e32 v203, 31, v180
	s_and_b32 s11, s5, 0x80
	s_mov_b32 s5, 0x20000
	v_lshrrev_b32_e32 v181, 5, v182
	s_mov_b64 s[8:9], 0
	s_waitcnt lgkmcnt(0)
	v_lshl_add_u64 v[26:27], s[54:55], 2, v[4:5]
	v_lshl_add_u64 v[2:3], v[8:9], 0, v[178:179]
	v_lshl_add_u64 v[4:5], v[2:3], 0, s[82:83]
	v_and_b32_e32 v2, 0x100, v40
	v_mov_b32_e32 v3, v179
	v_lshl_add_u64 v[10:11], v[4:5], 0, v[2:3]
	v_ashrrev_i32_e32 v4, 8, v180
	v_ashrrev_i32_e32 v5, 31, v4
	v_ashrrev_i32_e32 v238, 5, v180
	v_ashrrev_i32_e32 v240, 3, v238
	v_ashrrev_i32_e32 v241, 31, v240
	v_lshl_add_u64 v[240:241], v[240:241], 2, v[26:27]
	global_load_dword v230, v[240:241], off
	v_add_u32_e32 v239, 0x10, v238
	v_ashrrev_i32_e32 v240, 3, v239
	v_ashrrev_i32_e32 v241, 31, v240
	v_lshl_add_u64 v[240:241], v[240:241], 2, v[26:27]
	global_load_dword v231, v[240:241], off
	v_add_u32_e32 v239, 0x20, v238
	v_ashrrev_i32_e32 v240, 3, v239
	v_ashrrev_i32_e32 v241, 31, v240
	v_lshl_add_u64 v[240:241], v[240:241], 2, v[26:27]
	global_load_dword v232, v[240:241], off
	v_add_u32_e32 v239, 0x30, v238
	v_ashrrev_i32_e32 v240, 3, v239
	v_ashrrev_i32_e32 v241, 31, v240
	v_lshl_add_u64 v[240:241], v[240:241], 2, v[26:27]
	global_load_dword v233, v[240:241], off
	v_add_u32_e32 v239, 0x40, v238
	v_ashrrev_i32_e32 v240, 3, v239
	v_ashrrev_i32_e32 v241, 31, v240
	v_lshl_add_u64 v[240:241], v[240:241], 2, v[26:27]
	global_load_dword v234, v[240:241], off
	v_add_u32_e32 v239, 0x50, v238
	v_ashrrev_i32_e32 v240, 3, v239
	v_ashrrev_i32_e32 v241, 31, v240
	v_lshl_add_u64 v[240:241], v[240:241], 2, v[26:27]
	global_load_dword v235, v[240:241], off
	v_add_u32_e32 v239, 0x60, v238
	v_ashrrev_i32_e32 v240, 3, v239
	v_ashrrev_i32_e32 v241, 31, v240
	v_lshl_add_u64 v[240:241], v[240:241], 2, v[26:27]
	global_load_dword v236, v[240:241], off
	v_add_u32_e32 v239, 0x70, v238
	v_ashrrev_i32_e32 v240, 3, v239
	v_ashrrev_i32_e32 v241, 31, v240
	v_lshl_add_u64 v[240:241], v[240:241], 2, v[26:27]
	global_load_dword v237, v[240:241], off
	s_waitcnt vmcnt(0)
	v_lshl_add_u64 v[4:5], v[4:5], 2, v[26:27]
	v_mov_b32_e32 v4, v230
	v_add_u32_e32 v3, 16, v41
	v_lshl_add_u64 v[8:9], v[8:9], 0, s[76:77]
	s_waitcnt vmcnt(0)
	v_ashrrev_i32_e32 v5, 31, v4
	v_lshlrev_b64 v[4:5], 17, v[4:5]
	v_lshl_add_u64 v[12:13], v[10:11], 0, v[4:5]
	v_lshl_add_u64 v[18:19], v[12:13], 0, v[6:7]
	v_ashrrev_i32_e32 v12, 3, v3
	v_ashrrev_i32_e32 v13, 31, v12
	v_lshl_add_u64 v[12:13], v[12:13], 2, v[26:27]
	v_mov_b32_e32 v12, v231
	v_add_u32_e32 v3, 32, v41
	v_or_b32_e32 v4, v4, v178
	v_or3_b32 v4, v4, v2, v6
	v_lshl_add_u64 v[200:201], v[8:9], 0, v[4:5]
	s_waitcnt vmcnt(0)
	v_ashrrev_i32_e32 v13, 31, v12
	v_lshlrev_b64 v[12:13], 17, v[12:13]
	v_lshl_add_u64 v[14:15], v[10:11], 0, v[12:13]
	v_lshl_add_u64 v[22:23], v[14:15], 0, v[6:7]
	v_ashrrev_i32_e32 v14, 3, v3
	v_ashrrev_i32_e32 v15, 31, v14
	v_lshl_add_u64 v[14:15], v[14:15], 2, v[26:27]
	v_mov_b32_e32 v14, v232
	v_add_u32_e32 v3, 48, v41
	v_or_b32_e32 v12, v12, v178
	v_or3_b32 v12, v12, v2, v6
	v_lshl_add_u64 v[198:199], v[8:9], 0, v[12:13]
	s_waitcnt vmcnt(0)
	v_ashrrev_i32_e32 v15, 31, v14
	v_lshlrev_b64 v[14:15], 17, v[14:15]
	v_lshl_add_u64 v[16:17], v[10:11], 0, v[14:15]
	v_lshl_add_u64 v[28:29], v[16:17], 0, v[6:7]
	v_ashrrev_i32_e32 v16, 3, v3
	v_ashrrev_i32_e32 v17, 31, v16
	v_lshl_add_u64 v[16:17], v[16:17], 2, v[26:27]
	v_mov_b32_e32 v16, v233
	v_add_u32_e32 v3, 64, v41
	v_or_b32_e32 v14, v14, v178
	v_or3_b32 v14, v14, v2, v6
	v_lshl_add_u64 v[196:197], v[8:9], 0, v[14:15]
	s_waitcnt vmcnt(0)
	v_ashrrev_i32_e32 v17, 31, v16
	v_lshlrev_b64 v[16:17], 17, v[16:17]
	v_lshl_add_u64 v[20:21], v[10:11], 0, v[16:17]
	v_lshl_add_u64 v[32:33], v[20:21], 0, v[6:7]
	v_ashrrev_i32_e32 v20, 3, v3
	v_ashrrev_i32_e32 v21, 31, v20
	v_lshl_add_u64 v[20:21], v[20:21], 2, v[26:27]
	v_mov_b32_e32 v20, v234
	v_add_u32_e32 v3, 0x50, v41
	v_or_b32_e32 v16, v16, v178
	v_or3_b32 v16, v16, v2, v6
	v_lshl_add_u64 v[194:195], v[8:9], 0, v[16:17]
	s_waitcnt vmcnt(0)
	v_ashrrev_i32_e32 v21, 31, v20
	v_lshlrev_b64 v[20:21], 17, v[20:21]
	v_lshl_add_u64 v[24:25], v[10:11], 0, v[20:21]
	v_lshl_add_u64 v[34:35], v[24:25], 0, v[6:7]
	v_ashrrev_i32_e32 v24, 3, v3
	v_ashrrev_i32_e32 v25, 31, v24
	v_lshl_add_u64 v[24:25], v[24:25], 2, v[26:27]
	v_mov_b32_e32 v24, v235
	v_add_u32_e32 v3, 0x60, v41
	v_or_b32_e32 v20, v20, v178
	v_or3_b32 v20, v20, v2, v6
	v_lshl_add_u64 v[192:193], v[8:9], 0, v[20:21]
	s_waitcnt vmcnt(0)
	v_ashrrev_i32_e32 v25, 31, v24
	v_lshlrev_b64 v[24:25], 17, v[24:25]
	v_lshl_add_u64 v[30:31], v[10:11], 0, v[24:25]
	v_lshl_add_u64 v[36:37], v[30:31], 0, v[6:7]
	v_ashrrev_i32_e32 v30, 3, v3
	v_add_u32_e32 v3, 0x70, v41
	v_ashrrev_i32_e32 v42, 3, v3
	v_ashrrev_i32_e32 v31, 31, v30
	v_ashrrev_i32_e32 v43, 31, v42
	v_lshl_add_u64 v[30:31], v[30:31], 2, v[26:27]
	v_lshl_add_u64 v[26:27], v[42:43], 2, v[26:27]
	v_mov_b32_e32 v30, v236
	v_lshrrev_b32_e32 v3, 4, v180
	v_mov_b32_e32 v26, v237
	v_mul_lo_u32 v41, v3, s48
	v_lshlrev_b32_e32 v3, 3, v180
	v_and_b32_e32 v48, 0x78, v3
	v_or_b32_e32 v3, s6, v203
	s_waitcnt vmcnt(1)
	v_ashrrev_i32_e32 v31, 31, v30
	v_lshlrev_b64 v[30:31], 17, v[30:31]
	s_waitcnt vmcnt(0)
	v_ashrrev_i32_e32 v27, 31, v26
	v_lshlrev_b64 v[26:27], 17, v[26:27]
	v_lshl_add_u64 v[38:39], v[10:11], 0, v[30:31]
	v_lshl_add_u64 v[10:11], v[10:11], 0, v[26:27]
	v_lshl_add_u64 v[42:43], v[10:11], 0, v[6:7]
	v_ashrrev_i32_e32 v10, 3, v180
	v_ashrrev_i32_e32 v11, 31, v10
	v_lshl_add_u64 v[38:39], v[38:39], 0, v[6:7]
	v_lshlrev_b64 v[44:45], 11, v[10:11]
	v_or_b32_e32 v7, s11, v203
	v_mov_b32_e32 v11, s96
	v_lshl_add_u64 v[46:47], s[58:59], 0, v[44:45]
	v_mul_lo_u32 v49, v10, s48
	v_and_b32_e32 v10, 0x70, v40
	v_mad_u32_u24 v7, v7, s48, v11
	v_mov_b32_e32 v11, v179
	global_load_dwordx4 v[130:133], v[18:19], off nt
	global_load_dwordx4 v[134:137], v[22:23], off nt
	global_load_dwordx4 v[138:141], v[28:29], off nt
	global_load_dwordx4 v[142:145], v[32:33], off nt
	global_load_dwordx4 v[146:149], v[34:35], off nt
	global_load_dwordx4 v[150:153], v[36:37], off nt
	global_load_dwordx4 v[154:157], v[38:39], off nt
	global_load_dwordx4 v[158:161], v[42:43], off nt
	v_lshl_add_u64 v[22:23], v[46:47], 0, v[10:11]
	v_add_co_u32_e32 v28, vcc, s5, v22
	s_mov_b32 s5, 0x40000
	s_nop 0
	v_addc_co_u32_e32 v29, vcc, 0, v23, vcc
	global_load_dwordx4 v[162:165], v[22:23], off
	global_load_dwordx4 v[166:169], v[28:29], off
	v_add_co_u32_e32 v28, vcc, s5, v22
	s_mov_b32 s5, 0x60000
	s_nop 0
	v_addc_co_u32_e32 v29, vcc, 0, v23, vcc
	v_add_co_u32_e32 v22, vcc, s5, v22
	global_load_dwordx4 v[170:173], v[28:29], off
	s_nop 0
	v_addc_co_u32_e32 v23, vcc, 0, v23, vcc
	global_load_dwordx4 v[174:177], v[22:23], off
	v_or_b32_e32 v22, v26, v178
	v_or3_b32 v26, v22, v2, v6
	v_or_b32_e32 v22, v30, v178
	v_mul_lo_u32 v40, v3, s48
	v_or3_b32 v30, v22, v2, v6
	v_or_b32_e32 v22, v24, v178
	v_lshlrev_b32_e32 v3, 4, v181
	v_add_u32_e32 v19, s96, v41
	v_add_u32_e32 v11, s96, v49
	v_add_u32_e32 v18, s96, v40
	v_or_b32_e32 v44, v44, v10
	v_or3_b32 v24, v22, v2, v6
	v_mov_b32_e32 v2, 0
	v_lshl_add_u64 v[184:185], s[74:75], 0, v[44:45]
	v_lshl_add_u64 v[186:187], v[8:9], 0, v[26:27]
	v_lshl_add_u64 v[188:189], v[8:9], 0, v[30:31]
	v_lshl_add_u64 v[190:191], v[8:9], 0, v[24:25]
	v_add_u32_e32 v178, v19, v48
	v_add_u32_e32 v204, v11, v10
	v_add_u32_e32 v205, v18, v3
	v_add_u32_e32 v206, v7, v3
	v_mov_b32_e32 v3, v2
	v_mov_b32_e32 v4, v2
	v_mov_b32_e32 v5, v2
	v_mov_b32_e32 v6, v2
	v_mov_b32_e32 v7, v2
	v_mov_b32_e32 v8, v2
	v_mov_b32_e32 v9, v2
	v_mov_b32_e32 v10, v2
	v_mov_b32_e32 v11, v2
	v_mov_b32_e32 v12, v2
	v_mov_b32_e32 v13, v2
	v_mov_b32_e32 v14, v2
	v_mov_b32_e32 v15, v2
	v_mov_b32_e32 v16, v2
	v_mov_b32_e32 v17, v2
	v_mov_b32_e32 v18, v2
	v_mov_b32_e32 v19, v2
	v_mov_b32_e32 v20, v2
	v_mov_b32_e32 v21, v2
	v_mov_b32_e32 v22, v2
	v_mov_b32_e32 v23, v2
	v_mov_b32_e32 v24, v2
	v_mov_b32_e32 v25, v2
	v_mov_b32_e32 v26, v2
	v_mov_b32_e32 v27, v2
	v_mov_b32_e32 v28, v2
	v_mov_b32_e32 v29, v2
	v_mov_b32_e32 v30, v2
	v_mov_b32_e32 v31, v2
	v_mov_b32_e32 v32, v2
	v_mov_b32_e32 v33, v2
	v_mov_b32_e32 v34, v2
	v_mov_b32_e32 v35, v2
	v_mov_b32_e32 v36, v2
	v_mov_b32_e32 v37, v2
	v_mov_b32_e32 v38, v2
	v_mov_b32_e32 v39, v2
	v_mov_b32_e32 v40, v2
	v_mov_b32_e32 v41, v2
	v_mov_b32_e32 v42, v2
	v_mov_b32_e32 v43, v2
	v_mov_b32_e32 v44, v2
	v_mov_b32_e32 v45, v2
	v_mov_b32_e32 v46, v2
	v_mov_b32_e32 v47, v2
	v_mov_b32_e32 v48, v2
	v_mov_b32_e32 v49, v2
	v_mov_b32_e32 v50, v2
	v_mov_b32_e32 v51, v2
	v_mov_b32_e32 v52, v2
	v_mov_b32_e32 v53, v2
	v_mov_b32_e32 v54, v2
	v_mov_b32_e32 v55, v2
	v_mov_b32_e32 v56, v2
	v_mov_b32_e32 v57, v2
	v_mov_b32_e32 v58, v2
	v_mov_b32_e32 v59, v2
	v_mov_b32_e32 v60, v2
	v_mov_b32_e32 v61, v2
	v_mov_b32_e32 v62, v2
	v_mov_b32_e32 v63, v2
	v_mov_b32_e32 v64, v2
	v_mov_b32_e32 v65, v2
	v_mov_b32_e32 v66, v2
	v_mov_b32_e32 v67, v2
	v_mov_b32_e32 v68, v2
	v_mov_b32_e32 v69, v2
	v_mov_b32_e32 v70, v2
	v_mov_b32_e32 v71, v2
	v_mov_b32_e32 v72, v2
	v_mov_b32_e32 v73, v2
	v_mov_b32_e32 v74, v2
	v_mov_b32_e32 v75, v2
	v_mov_b32_e32 v76, v2
	v_mov_b32_e32 v77, v2
	v_mov_b32_e32 v78, v2
	v_mov_b32_e32 v79, v2
	v_mov_b32_e32 v80, v2
	v_mov_b32_e32 v81, v2
	v_mov_b32_e32 v82, v2
	v_mov_b32_e32 v83, v2
	v_mov_b32_e32 v84, v2
	v_mov_b32_e32 v85, v2
	v_mov_b32_e32 v86, v2
	v_mov_b32_e32 v87, v2
	v_mov_b32_e32 v88, v2
	v_mov_b32_e32 v89, v2
	v_mov_b32_e32 v90, v2
	v_mov_b32_e32 v91, v2
	v_mov_b32_e32 v92, v2
	v_mov_b32_e32 v93, v2
	v_mov_b32_e32 v94, v2
	v_mov_b32_e32 v95, v2
	v_mov_b32_e32 v96, v2
	v_mov_b32_e32 v97, v2
	v_mov_b32_e32 v98, v2
	v_mov_b32_e32 v99, v2
	v_mov_b32_e32 v100, v2
	v_mov_b32_e32 v101, v2
	v_mov_b32_e32 v102, v2
	v_mov_b32_e32 v103, v2
	v_mov_b32_e32 v104, v2
	v_mov_b32_e32 v105, v2
	v_mov_b32_e32 v106, v2
	v_mov_b32_e32 v107, v2
	v_mov_b32_e32 v108, v2
	v_mov_b32_e32 v109, v2
	v_mov_b32_e32 v110, v2
	v_mov_b32_e32 v111, v2
	v_mov_b32_e32 v112, v2
	v_mov_b32_e32 v113, v2
	v_mov_b32_e32 v114, v2
	v_mov_b32_e32 v115, v2
	v_mov_b32_e32 v116, v2
	v_mov_b32_e32 v117, v2
	v_mov_b32_e32 v118, v2
	v_mov_b32_e32 v119, v2
	v_mov_b32_e32 v120, v2
	v_mov_b32_e32 v121, v2
	v_mov_b32_e32 v122, v2
	v_mov_b32_e32 v123, v2
	v_mov_b32_e32 v124, v2
	v_mov_b32_e32 v125, v2
	v_mov_b32_e32 v126, v2
	v_mov_b32_e32 v127, v2
	v_mov_b32_e32 v128, v2
	v_mov_b32_e32 v129, v2
	global_load_dwordx4 v[220:223], v[200:201], off nt
	s_nop 0
	global_load_dwordx4 v[224:227], v[198:199], off nt
	s_nop 0
	global_load_dwordx4 v[230:233], v[196:197], off nt
	s_nop 0
	global_load_dwordx4 v[234:237], v[194:195], off nt
	s_nop 0
	global_load_dwordx4 v[238:241], v[192:193], off nt
	s_nop 0
	global_load_dwordx4 v[242:245], v[190:191], off nt
	s_nop 0
	global_load_dwordx4 v[246:249], v[188:189], off nt
	s_nop 0
	global_load_dwordx4 v[250:253], v[186:187], off nt
	s_nop 0
	s_branch .LBB0_1594
.LBB0_1594:
	s_waitcnt vmcnt(8)
	v_cvt_pk_bf16_f32 v208, v130, v131
	v_cvt_pk_bf16_f32 v209, v132, v133
	v_cvt_pk_bf16_f32 v210, v134, v135
	v_cvt_pk_bf16_f32 v211, v136, v137
	s_waitcnt lgkmcnt(0)
	s_barrier
	ds_write2st64_b64 v178, v[208:209], v[210:211] offset1:9
	v_cvt_pk_bf16_f32 v208, v138, v139
	v_cvt_pk_bf16_f32 v209, v140, v141
	v_cvt_pk_bf16_f32 v210, v142, v143
	v_cvt_pk_bf16_f32 v211, v144, v145
	ds_write2st64_b64 v178, v[208:209], v[210:211] offset0:18 offset1:27
	v_cvt_pk_bf16_f32 v208, v146, v147
	v_cvt_pk_bf16_f32 v209, v148, v149
	v_cvt_pk_bf16_f32 v210, v150, v151
	v_cvt_pk_bf16_f32 v211, v152, v153
	ds_write2st64_b64 v178, v[208:209], v[210:211] offset0:36 offset1:45
	v_cvt_pk_bf16_f32 v208, v154, v155
	v_cvt_pk_bf16_f32 v209, v156, v157
	v_cvt_pk_bf16_f32 v210, v158, v159
	v_cvt_pk_bf16_f32 v211, v160, v161
	s_cmpk_eq_i32 s8, 0x3c00
	ds_write2st64_b64 v178, v[208:209], v[210:211] offset0:54 offset1:63
	ds_write_b128 v204, v[162:165] offset:36864
	ds_write_b128 v204, v[166:169] offset:46080
	ds_write_b128 v204, v[170:173] offset:55296
	ds_write_b128 v204, v[174:177] offset:64512
	s_waitcnt lgkmcnt(0)
	s_barrier
	s_add_u32 s98, s8, 0x400
	s_min_u32 s98, s98, 0x3800
	s_mov_b32 s99, 0
	v_add_co_u32_e32 v162, vcc, 0xfffa0000, v184
	v_lshl_add_u64 v[130:131], v[200:201], 0, s[98:99]
	s_nop 0
	v_addc_co_u32_e32 v163, vcc, -1, v185, vcc
	v_add_co_u32_e32 v166, vcc, 0xfffc0000, v184
	v_lshl_add_u64 v[134:135], v[198:199], 0, s[98:99]
	s_nop 0
	v_addc_co_u32_e32 v167, vcc, -1, v185, vcc
	v_add_co_u32_e32 v170, vcc, 0xfffe0000, v184
	v_lshl_add_u64 v[138:139], v[196:197], 0, s[98:99]
	v_lshl_add_u64 v[142:143], v[194:195], 0, s[98:99]
	v_lshl_add_u64 v[146:147], v[192:193], 0, s[98:99]
	v_lshl_add_u64 v[150:151], v[190:191], 0, s[98:99]
	v_lshl_add_u64 v[154:155], v[188:189], 0, s[98:99]
	v_lshl_add_u64 v[158:159], v[186:187], 0, s[98:99]
	v_addc_co_u32_e32 v171, vcc, -1, v185, vcc
	global_load_dwordx4 v[162:165], v[162:163], off
	s_nop 0
	global_load_dwordx4 v[166:169], v[166:167], off
	s_nop 0
	global_load_dwordx4 v[170:173], v[170:171], off
	s_nop 0
	global_load_dwordx4 v[174:177], v[184:185], off
	s_nop 0
	global_load_dwordx4 v[130:133], v[130:131], off nt
	s_nop 0
	global_load_dwordx4 v[134:137], v[134:135], off nt
	s_nop 0
	global_load_dwordx4 v[138:141], v[138:139], off nt
	s_nop 0
	global_load_dwordx4 v[142:145], v[142:143], off nt
	s_nop 0
	global_load_dwordx4 v[146:149], v[146:147], off nt
	s_nop 0
	global_load_dwordx4 v[150:153], v[150:151], off nt
	s_nop 0
	global_load_dwordx4 v[154:157], v[154:155], off nt
	s_nop 0
	global_load_dwordx4 v[158:161], v[158:159], off nt
	s_nop 0
	ds_read_b128 v[208:211], v205
	ds_read_b128 v[212:215], v206 offset:36864
	ds_read_b128 v[216:219], v205 offset:4608
	s_add_u32 s8, s8, 0x400
	s_addc_u32 s9, s9, 0
	v_lshl_add_u64 v[184:185], v[184:185], 0, s[84:85]
	s_waitcnt lgkmcnt(0)
	v_mfma_f32_32x32x16_bf16 v[114:129], v[208:211], v[212:215], v[114:129]
	s_cmpk_lg_i32 s8, 0x4000
	v_mfma_f32_32x32x16_bf16 v[50:65], v[216:219], v[212:215], v[50:65]
	ds_read_b128 v[212:215], v206 offset:41472
	s_waitcnt lgkmcnt(0)
	v_mfma_f32_32x32x16_bf16 v[98:113], v[208:211], v[212:215], v[98:113]
	v_mfma_f32_32x32x16_bf16 v[34:49], v[216:219], v[212:215], v[34:49]
	ds_read_b128 v[212:215], v206 offset:46080
	s_waitcnt lgkmcnt(0)
	v_mfma_f32_32x32x16_bf16 v[82:97], v[208:211], v[212:215], v[82:97]
	v_mfma_f32_32x32x16_bf16 v[18:33], v[216:219], v[212:215], v[18:33]
	ds_read_b128 v[212:215], v206 offset:50688
	s_waitcnt lgkmcnt(0)
	v_mfma_f32_32x32x16_bf16 v[66:81], v[208:211], v[212:215], v[66:81]
	v_mfma_f32_32x32x16_bf16 v[2:17], v[216:219], v[212:215], v[2:17]
	ds_read_b128 v[208:211], v205 offset:32
	ds_read_b128 v[212:215], v206 offset:36896
	ds_read_b128 v[216:219], v205 offset:4640
	s_waitcnt lgkmcnt(0)
	v_mfma_f32_32x32x16_bf16 v[114:129], v[208:211], v[212:215], v[114:129]
	v_mfma_f32_32x32x16_bf16 v[50:65], v[216:219], v[212:215], v[50:65]
	ds_read_b128 v[212:215], v206 offset:41504
	s_waitcnt lgkmcnt(0)
	v_mfma_f32_32x32x16_bf16 v[98:113], v[208:211], v[212:215], v[98:113]
	v_mfma_f32_32x32x16_bf16 v[34:49], v[216:219], v[212:215], v[34:49]
	ds_read_b128 v[212:215], v206 offset:46112
	s_waitcnt lgkmcnt(0)
	v_mfma_f32_32x32x16_bf16 v[82:97], v[208:211], v[212:215], v[82:97]
	v_mfma_f32_32x32x16_bf16 v[18:33], v[216:219], v[212:215], v[18:33]
	ds_read_b128 v[212:215], v206 offset:50720
	s_waitcnt lgkmcnt(0)
	v_mfma_f32_32x32x16_bf16 v[66:81], v[208:211], v[212:215], v[66:81]
	v_mfma_f32_32x32x16_bf16 v[2:17], v[216:219], v[212:215], v[2:17]
	ds_read_b128 v[208:211], v205 offset:64
	ds_read_b128 v[212:215], v206 offset:36928
	ds_read_b128 v[216:219], v205 offset:4672
	s_waitcnt lgkmcnt(0)
	v_mfma_f32_32x32x16_bf16 v[114:129], v[208:211], v[212:215], v[114:129]
	v_mfma_f32_32x32x16_bf16 v[50:65], v[216:219], v[212:215], v[50:65]
	ds_read_b128 v[212:215], v206 offset:41536
	s_waitcnt lgkmcnt(0)
	v_mfma_f32_32x32x16_bf16 v[98:113], v[208:211], v[212:215], v[98:113]
	v_mfma_f32_32x32x16_bf16 v[34:49], v[216:219], v[212:215], v[34:49]
	ds_read_b128 v[212:215], v206 offset:46144
	s_waitcnt lgkmcnt(0)
	v_mfma_f32_32x32x16_bf16 v[82:97], v[208:211], v[212:215], v[82:97]
	v_mfma_f32_32x32x16_bf16 v[18:33], v[216:219], v[212:215], v[18:33]
	ds_read_b128 v[212:215], v206 offset:50752
	s_waitcnt lgkmcnt(0)
	v_mfma_f32_32x32x16_bf16 v[66:81], v[208:211], v[212:215], v[66:81]
	v_mfma_f32_32x32x16_bf16 v[2:17], v[216:219], v[212:215], v[2:17]
	ds_read_b128 v[208:211], v205 offset:96
	ds_read_b128 v[212:215], v206 offset:36960
	ds_read_b128 v[216:219], v205 offset:4704
	s_waitcnt lgkmcnt(0)
	v_mfma_f32_32x32x16_bf16 v[114:129], v[208:211], v[212:215], v[114:129]
	v_mfma_f32_32x32x16_bf16 v[50:65], v[216:219], v[212:215], v[50:65]
	ds_read_b128 v[212:215], v206 offset:41568
	s_waitcnt lgkmcnt(0)
	v_mfma_f32_32x32x16_bf16 v[98:113], v[208:211], v[212:215], v[98:113]
	v_mfma_f32_32x32x16_bf16 v[34:49], v[216:219], v[212:215], v[34:49]
	ds_read_b128 v[212:215], v206 offset:46176
	s_waitcnt lgkmcnt(0)
	v_mfma_f32_32x32x16_bf16 v[82:97], v[208:211], v[212:215], v[82:97]
	v_mfma_f32_32x32x16_bf16 v[18:33], v[216:219], v[212:215], v[18:33]
	ds_read_b128 v[212:215], v206 offset:50784
	s_waitcnt lgkmcnt(0)
	v_mfma_f32_32x32x16_bf16 v[66:81], v[208:211], v[212:215], v[66:81]
	v_mfma_f32_32x32x16_bf16 v[2:17], v[216:219], v[212:215], v[2:17]
.Lmy_cfu0_odd:
	s_waitcnt vmcnt(8)
	v_cvt_pk_bf16_f32 v208, v220, v221
	v_cvt_pk_bf16_f32 v209, v222, v223
	v_cvt_pk_bf16_f32 v210, v224, v225
	v_cvt_pk_bf16_f32 v211, v226, v227
	s_waitcnt lgkmcnt(0)
	s_barrier
	ds_write2st64_b64 v178, v[208:209], v[210:211] offset1:9
	v_cvt_pk_bf16_f32 v208, v230, v231
	v_cvt_pk_bf16_f32 v209, v232, v233
	v_cvt_pk_bf16_f32 v210, v234, v235
	v_cvt_pk_bf16_f32 v211, v236, v237
	ds_write2st64_b64 v178, v[208:209], v[210:211] offset0:18 offset1:27
	v_cvt_pk_bf16_f32 v208, v238, v239
	v_cvt_pk_bf16_f32 v209, v240, v241
	v_cvt_pk_bf16_f32 v210, v242, v243
	v_cvt_pk_bf16_f32 v211, v244, v245
	ds_write2st64_b64 v178, v[208:209], v[210:211] offset0:36 offset1:45
	v_cvt_pk_bf16_f32 v208, v246, v247
	v_cvt_pk_bf16_f32 v209, v248, v249
	v_cvt_pk_bf16_f32 v210, v250, v251
	v_cvt_pk_bf16_f32 v211, v252, v253
	s_cmpk_eq_i32 s8, 0x3c00
	ds_write2st64_b64 v178, v[208:209], v[210:211] offset0:54 offset1:63
	ds_write_b128 v204, v[162:165] offset:36864
	ds_write_b128 v204, v[166:169] offset:46080
	ds_write_b128 v204, v[170:173] offset:55296
	ds_write_b128 v204, v[174:177] offset:64512
	s_waitcnt lgkmcnt(0)
	s_barrier
	s_cbranch_scc1 .Lmy_cfu0_mm
	s_add_u32 s98, s8, 0x400
	s_min_u32 s98, s98, 0x3800
	s_mov_b32 s99, 0
	v_add_co_u32_e32 v162, vcc, 0xfffa0000, v184
	v_lshl_add_u64 v[220:221], v[200:201], 0, s[98:99]
	s_nop 0
	v_addc_co_u32_e32 v163, vcc, -1, v185, vcc
	v_add_co_u32_e32 v166, vcc, 0xfffc0000, v184
	v_lshl_add_u64 v[224:225], v[198:199], 0, s[98:99]
	s_nop 0
	v_addc_co_u32_e32 v167, vcc, -1, v185, vcc
	v_add_co_u32_e32 v170, vcc, 0xfffe0000, v184
	v_lshl_add_u64 v[230:231], v[196:197], 0, s[98:99]
	v_lshl_add_u64 v[234:235], v[194:195], 0, s[98:99]
	v_lshl_add_u64 v[238:239], v[192:193], 0, s[98:99]
	v_lshl_add_u64 v[242:243], v[190:191], 0, s[98:99]
	v_lshl_add_u64 v[246:247], v[188:189], 0, s[98:99]
	v_lshl_add_u64 v[250:251], v[186:187], 0, s[98:99]
	v_addc_co_u32_e32 v171, vcc, -1, v185, vcc
	global_load_dwordx4 v[162:165], v[162:163], off
	s_nop 0
	global_load_dwordx4 v[166:169], v[166:167], off
	s_nop 0
	global_load_dwordx4 v[170:173], v[170:171], off
	s_nop 0
	global_load_dwordx4 v[174:177], v[184:185], off
	s_nop 0
	global_load_dwordx4 v[220:223], v[220:221], off nt
	s_nop 0
	global_load_dwordx4 v[224:227], v[224:225], off nt
	s_nop 0
	global_load_dwordx4 v[230:233], v[230:231], off nt
	s_nop 0
	global_load_dwordx4 v[234:237], v[234:235], off nt
	s_nop 0
	global_load_dwordx4 v[238:241], v[238:239], off nt
	s_nop 0
	global_load_dwordx4 v[242:245], v[242:243], off nt
	s_nop 0
	global_load_dwordx4 v[246:249], v[246:247], off nt
	s_nop 0
	global_load_dwordx4 v[250:253], v[250:251], off nt
	s_nop 0
.Lmy_cfu0_mm:
	ds_read_b128 v[208:211], v205
	ds_read_b128 v[212:215], v206 offset:36864
	ds_read_b128 v[216:219], v205 offset:4608
	s_add_u32 s8, s8, 0x400
	s_addc_u32 s9, s9, 0
	v_lshl_add_u64 v[184:185], v[184:185], 0, s[84:85]
	s_waitcnt lgkmcnt(0)
	v_mfma_f32_32x32x16_bf16 v[114:129], v[208:211], v[212:215], v[114:129]
	s_cmpk_lg_i32 s8, 0x4000
	v_mfma_f32_32x32x16_bf16 v[50:65], v[216:219], v[212:215], v[50:65]
	ds_read_b128 v[212:215], v206 offset:41472
	s_waitcnt lgkmcnt(0)
	v_mfma_f32_32x32x16_bf16 v[98:113], v[208:211], v[212:215], v[98:113]
	v_mfma_f32_32x32x16_bf16 v[34:49], v[216:219], v[212:215], v[34:49]
	ds_read_b128 v[212:215], v206 offset:46080
	s_waitcnt lgkmcnt(0)
	v_mfma_f32_32x32x16_bf16 v[82:97], v[208:211], v[212:215], v[82:97]
	v_mfma_f32_32x32x16_bf16 v[18:33], v[216:219], v[212:215], v[18:33]
	ds_read_b128 v[212:215], v206 offset:50688
	s_waitcnt lgkmcnt(0)
	v_mfma_f32_32x32x16_bf16 v[66:81], v[208:211], v[212:215], v[66:81]
	v_mfma_f32_32x32x16_bf16 v[2:17], v[216:219], v[212:215], v[2:17]
	ds_read_b128 v[208:211], v205 offset:32
	ds_read_b128 v[212:215], v206 offset:36896
	ds_read_b128 v[216:219], v205 offset:4640
	s_waitcnt lgkmcnt(0)
	v_mfma_f32_32x32x16_bf16 v[114:129], v[208:211], v[212:215], v[114:129]
	v_mfma_f32_32x32x16_bf16 v[50:65], v[216:219], v[212:215], v[50:65]
	ds_read_b128 v[212:215], v206 offset:41504
	s_waitcnt lgkmcnt(0)
	v_mfma_f32_32x32x16_bf16 v[98:113], v[208:211], v[212:215], v[98:113]
	v_mfma_f32_32x32x16_bf16 v[34:49], v[216:219], v[212:215], v[34:49]
	ds_read_b128 v[212:215], v206 offset:46112
	s_waitcnt lgkmcnt(0)
	v_mfma_f32_32x32x16_bf16 v[82:97], v[208:211], v[212:215], v[82:97]
	v_mfma_f32_32x32x16_bf16 v[18:33], v[216:219], v[212:215], v[18:33]
	ds_read_b128 v[212:215], v206 offset:50720
	s_waitcnt lgkmcnt(0)
	v_mfma_f32_32x32x16_bf16 v[66:81], v[208:211], v[212:215], v[66:81]
	v_mfma_f32_32x32x16_bf16 v[2:17], v[216:219], v[212:215], v[2:17]
	ds_read_b128 v[208:211], v205 offset:64
	ds_read_b128 v[212:215], v206 offset:36928
	ds_read_b128 v[216:219], v205 offset:4672
	s_waitcnt lgkmcnt(0)
	v_mfma_f32_32x32x16_bf16 v[114:129], v[208:211], v[212:215], v[114:129]
	v_mfma_f32_32x32x16_bf16 v[50:65], v[216:219], v[212:215], v[50:65]
	ds_read_b128 v[212:215], v206 offset:41536
	s_waitcnt lgkmcnt(0)
	v_mfma_f32_32x32x16_bf16 v[98:113], v[208:211], v[212:215], v[98:113]
	v_mfma_f32_32x32x16_bf16 v[34:49], v[216:219], v[212:215], v[34:49]
	ds_read_b128 v[212:215], v206 offset:46144
	s_waitcnt lgkmcnt(0)
	v_mfma_f32_32x32x16_bf16 v[82:97], v[208:211], v[212:215], v[82:97]
	v_mfma_f32_32x32x16_bf16 v[18:33], v[216:219], v[212:215], v[18:33]
	ds_read_b128 v[212:215], v206 offset:50752
	s_waitcnt lgkmcnt(0)
	v_mfma_f32_32x32x16_bf16 v[66:81], v[208:211], v[212:215], v[66:81]
	v_mfma_f32_32x32x16_bf16 v[2:17], v[216:219], v[212:215], v[2:17]
	ds_read_b128 v[208:211], v205 offset:96
	ds_read_b128 v[212:215], v206 offset:36960
	ds_read_b128 v[216:219], v205 offset:4704
	s_waitcnt lgkmcnt(0)
	v_mfma_f32_32x32x16_bf16 v[114:129], v[208:211], v[212:215], v[114:129]
	v_mfma_f32_32x32x16_bf16 v[50:65], v[216:219], v[212:215], v[50:65]
	ds_read_b128 v[212:215], v206 offset:41568
	s_waitcnt lgkmcnt(0)
	v_mfma_f32_32x32x16_bf16 v[98:113], v[208:211], v[212:215], v[98:113]
	v_mfma_f32_32x32x16_bf16 v[34:49], v[216:219], v[212:215], v[34:49]
	ds_read_b128 v[212:215], v206 offset:46176
	s_waitcnt lgkmcnt(0)
	v_mfma_f32_32x32x16_bf16 v[82:97], v[208:211], v[212:215], v[82:97]
	v_mfma_f32_32x32x16_bf16 v[18:33], v[216:219], v[212:215], v[18:33]
	ds_read_b128 v[212:215], v206 offset:50784
	s_waitcnt lgkmcnt(0)
	v_mfma_f32_32x32x16_bf16 v[66:81], v[208:211], v[212:215], v[66:81]
	v_mfma_f32_32x32x16_bf16 v[2:17], v[216:219], v[212:215], v[2:17]
	s_cbranch_scc1 .LBB0_1594

.LBB0_4198:
	v_mov_b32_e32 v180, v0
	s_mov_b64 s[6:7], -1
	v_readfirstlane_b32 s22, v180
	s_ashr_i32 s10, s22, 6
	v_and_b32_e32 v182, 63, v180
	s_cmp_eq_u32 s2, s33
	s_cbranch_scc1 .LBB0_4204
	s_waitcnt lgkmcnt(0)
	v_mov_b64_e32 v[2:3], s[0:1]
	s_load_dwordx2 s[98:99], s[0:1], 0x40
	s_waitcnt vmcnt(0) lgkmcnt(0)
	v_mov_b32_e32 v4, s98
	v_mov_b32_e32 v5, s99
	s_load_dwordx2 s[98:99], s[0:1], 0x20
	s_waitcnt vmcnt(0) lgkmcnt(0)
	v_mov_b32_e32 v8, s98
	v_mov_b32_e32 v9, s99
	v_ashrrev_i32_e32 v41, 5, v180
	v_lshlrev_b32_e32 v2, 14, v41
	v_and_b32_e32 v178, 0x1c000, v2
	s_mov_b32 s81, s57
	v_lshlrev_b32_e32 v40, 4, v180
	s_mov_b64 s[6:7], 0x14000000
	v_and_b32_e32 v6, 0xf0, v40
	v_mov_b32_e32 v7, v179
	s_lshl_b32 s2, s10, 5
	v_and_b32_e32 v203, 31, v180
	v_lshrrev_b32_e32 v181, 5, v182
	s_mov_b64 s[8:9], 0
	s_waitcnt lgkmcnt(0)
	v_lshl_add_u64 v[24:25], s[54:55], 2, v[4:5]
	v_lshl_add_u64 v[2:3], v[8:9], 0, v[178:179]
	v_lshl_add_u64 v[4:5], v[2:3], 0, s[80:81]
	v_and_b32_e32 v2, 0x100, v40
	v_mov_b32_e32 v3, v179
	v_lshl_add_u64 v[4:5], v[4:5], 0, v[2:3]
	v_lshl_add_u64 v[10:11], v[4:5], 0, s[6:7]
	v_ashrrev_i32_e32 v4, 8, v180
	v_ashrrev_i32_e32 v5, 31, v4
	v_ashrrev_i32_e32 v238, 5, v180
	v_ashrrev_i32_e32 v240, 3, v238
	v_ashrrev_i32_e32 v241, 31, v240
	v_lshl_add_u64 v[240:241], v[240:241], 2, v[24:25]
	global_load_dword v230, v[240:241], off
	v_add_u32_e32 v239, 0x10, v238
	v_ashrrev_i32_e32 v240, 3, v239
	v_ashrrev_i32_e32 v241, 31, v240
	v_lshl_add_u64 v[240:241], v[240:241], 2, v[24:25]
	global_load_dword v231, v[240:241], off
	v_add_u32_e32 v239, 0x20, v238
	v_ashrrev_i32_e32 v240, 3, v239
	v_ashrrev_i32_e32 v241, 31, v240
	v_lshl_add_u64 v[240:241], v[240:241], 2, v[24:25]
	global_load_dword v232, v[240:241], off
	v_add_u32_e32 v239, 0x30, v238
	v_ashrrev_i32_e32 v240, 3, v239
	v_ashrrev_i32_e32 v241, 31, v240
	v_lshl_add_u64 v[240:241], v[240:241], 2, v[24:25]
	global_load_dword v233, v[240:241], off
	v_add_u32_e32 v239, 0x40, v238
	v_ashrrev_i32_e32 v240, 3, v239
	v_ashrrev_i32_e32 v241, 31, v240
	v_lshl_add_u64 v[240:241], v[240:241], 2, v[24:25]
	global_load_dword v234, v[240:241], off
	v_add_u32_e32 v239, 0x50, v238
	v_ashrrev_i32_e32 v240, 3, v239
	v_ashrrev_i32_e32 v241, 31, v240
	v_lshl_add_u64 v[240:241], v[240:241], 2, v[24:25]
	global_load_dword v235, v[240:241], off
	v_add_u32_e32 v239, 0x60, v238
	v_ashrrev_i32_e32 v240, 3, v239
	v_ashrrev_i32_e32 v241, 31, v240
	v_lshl_add_u64 v[240:241], v[240:241], 2, v[24:25]
	global_load_dword v236, v[240:241], off
	v_add_u32_e32 v239, 0x70, v238
	v_ashrrev_i32_e32 v240, 3, v239
	v_ashrrev_i32_e32 v241, 31, v240
	v_lshl_add_u64 v[240:241], v[240:241], 2, v[24:25]
	global_load_dword v237, v[240:241], off
	s_waitcnt vmcnt(0)
	v_lshl_add_u64 v[4:5], v[4:5], 2, v[24:25]
	v_mov_b32_e32 v4, v230
	v_add_u32_e32 v3, 16, v41
	s_and_b32 s6, s2, 0xffffffc0
	s_lshl_b32 s2, s10, 7
	s_and_b32 s11, s2, 0x80
	s_mov_b32 s2, 0x20000
	v_lshl_add_u64 v[8:9], v[8:9], 0, s[76:77]
	s_waitcnt vmcnt(0)
	v_ashrrev_i32_e32 v5, 31, v4
	v_lshlrev_b64 v[4:5], 17, v[4:5]
	v_lshl_add_u64 v[12:13], v[10:11], 0, v[4:5]
	v_lshl_add_u64 v[18:19], v[12:13], 0, v[6:7]
	v_ashrrev_i32_e32 v12, 3, v3
	v_ashrrev_i32_e32 v13, 31, v12
	v_lshl_add_u64 v[12:13], v[12:13], 2, v[24:25]
	v_mov_b32_e32 v12, v231
	v_add_u32_e32 v3, 32, v41
	v_or_b32_e32 v4, v4, v178
	v_or3_b32 v4, v4, v2, v6
	v_lshl_add_u64 v[200:201], v[8:9], 0, v[4:5]
	s_waitcnt vmcnt(0)
	v_ashrrev_i32_e32 v13, 31, v12
	v_lshlrev_b64 v[12:13], 17, v[12:13]
	v_lshl_add_u64 v[14:15], v[10:11], 0, v[12:13]
	v_lshl_add_u64 v[22:23], v[14:15], 0, v[6:7]
	v_ashrrev_i32_e32 v14, 3, v3
	v_ashrrev_i32_e32 v15, 31, v14
	v_lshl_add_u64 v[14:15], v[14:15], 2, v[24:25]
	v_mov_b32_e32 v14, v232
	v_add_u32_e32 v3, 48, v41
	v_or_b32_e32 v12, v12, v178
	v_or3_b32 v12, v12, v2, v6
	v_lshl_add_u64 v[198:199], v[8:9], 0, v[12:13]
	s_waitcnt vmcnt(0)
	v_ashrrev_i32_e32 v15, 31, v14
	v_lshlrev_b64 v[14:15], 17, v[14:15]
	v_lshl_add_u64 v[16:17], v[10:11], 0, v[14:15]
	v_lshl_add_u64 v[28:29], v[16:17], 0, v[6:7]
	v_ashrrev_i32_e32 v16, 3, v3
	v_ashrrev_i32_e32 v17, 31, v16
	v_lshl_add_u64 v[16:17], v[16:17], 2, v[24:25]
	v_mov_b32_e32 v16, v233
	v_add_u32_e32 v3, 64, v41
	v_or_b32_e32 v14, v14, v178
	v_or3_b32 v14, v14, v2, v6
	v_lshl_add_u64 v[196:197], v[8:9], 0, v[14:15]
	s_waitcnt vmcnt(0)
	v_ashrrev_i32_e32 v17, 31, v16
	v_lshlrev_b64 v[16:17], 17, v[16:17]
	v_lshl_add_u64 v[20:21], v[10:11], 0, v[16:17]
	v_lshl_add_u64 v[32:33], v[20:21], 0, v[6:7]
	v_ashrrev_i32_e32 v20, 3, v3
	v_ashrrev_i32_e32 v21, 31, v20
	v_lshl_add_u64 v[20:21], v[20:21], 2, v[24:25]
	v_mov_b32_e32 v20, v234
	v_add_u32_e32 v3, 0x50, v41
	v_or_b32_e32 v16, v16, v178
	v_or3_b32 v16, v16, v2, v6
	v_lshl_add_u64 v[194:195], v[8:9], 0, v[16:17]
	s_waitcnt vmcnt(0)
	v_ashrrev_i32_e32 v21, 31, v20
	v_lshlrev_b64 v[20:21], 17, v[20:21]
	v_lshl_add_u64 v[26:27], v[10:11], 0, v[20:21]
	v_lshl_add_u64 v[34:35], v[26:27], 0, v[6:7]
	v_ashrrev_i32_e32 v26, 3, v3
	v_ashrrev_i32_e32 v27, 31, v26
	v_lshl_add_u64 v[26:27], v[26:27], 2, v[24:25]
	v_mov_b32_e32 v26, v235
	v_add_u32_e32 v3, 0x60, v41
	v_or_b32_e32 v20, v20, v178
	v_or3_b32 v20, v20, v2, v6
	v_lshl_add_u64 v[192:193], v[8:9], 0, v[20:21]
	s_waitcnt vmcnt(0)
	v_ashrrev_i32_e32 v27, 31, v26
	v_lshlrev_b64 v[26:27], 17, v[26:27]
	v_lshl_add_u64 v[30:31], v[10:11], 0, v[26:27]
	v_lshl_add_u64 v[36:37], v[30:31], 0, v[6:7]
	v_ashrrev_i32_e32 v30, 3, v3
	v_add_u32_e32 v3, 0x70, v41
	v_ashrrev_i32_e32 v42, 3, v3
	v_ashrrev_i32_e32 v31, 31, v30
	v_ashrrev_i32_e32 v43, 31, v42
	v_lshl_add_u64 v[30:31], v[30:31], 2, v[24:25]
	v_lshl_add_u64 v[24:25], v[42:43], 2, v[24:25]
	v_mov_b32_e32 v30, v236
	v_lshrrev_b32_e32 v3, 4, v180
	v_mov_b32_e32 v24, v237
	v_mul_lo_u32 v41, v3, s48
	v_lshlrev_b32_e32 v3, 3, v180
	v_and_b32_e32 v3, 0x78, v3
	s_waitcnt vmcnt(1)
	v_ashrrev_i32_e32 v31, 31, v30
	v_lshlrev_b64 v[30:31], 17, v[30:31]
	s_waitcnt vmcnt(0)
	v_ashrrev_i32_e32 v25, 31, v24
	v_lshlrev_b64 v[24:25], 17, v[24:25]
	v_lshl_add_u64 v[38:39], v[10:11], 0, v[30:31]
	v_lshl_add_u64 v[10:11], v[10:11], 0, v[24:25]
	v_lshl_add_u64 v[42:43], v[10:11], 0, v[6:7]
	v_ashrrev_i32_e32 v10, 3, v180
	v_ashrrev_i32_e32 v11, 31, v10
	v_lshlrev_b64 v[44:45], 11, v[10:11]
	v_mul_lo_u32 v48, v10, s48
	v_and_b32_e32 v10, 0x70, v40
	v_or_b32_e32 v11, s11, v203
	v_mov_b32_e32 v40, s94
	v_lshl_add_u64 v[46:47], s[58:59], 0, v[44:45]
	v_mad_u32_u24 v40, v11, s48, v40
	v_mov_b32_e32 v11, v179
	v_lshl_add_u64 v[38:39], v[38:39], 0, v[6:7]
	global_load_dwordx4 v[130:133], v[18:19], off nt
	global_load_dwordx4 v[134:137], v[22:23], off nt
	global_load_dwordx4 v[138:141], v[28:29], off nt
	global_load_dwordx4 v[142:145], v[32:33], off nt
	global_load_dwordx4 v[146:149], v[34:35], off nt
	global_load_dwordx4 v[150:153], v[36:37], off nt
	global_load_dwordx4 v[154:157], v[38:39], off nt
	global_load_dwordx4 v[158:161], v[42:43], off nt
	v_lshl_add_u64 v[22:23], v[46:47], 0, v[10:11]
	v_add_co_u32_e32 v28, vcc, s2, v22
	s_mov_b32 s2, 0x40000
	s_nop 0
	v_addc_co_u32_e32 v29, vcc, 0, v23, vcc
	global_load_dwordx4 v[162:165], v[22:23], off
	global_load_dwordx4 v[166:169], v[28:29], off
	v_add_co_u32_e32 v28, vcc, s2, v22
	s_mov_b32 s2, 0x60000
	s_nop 0
	v_addc_co_u32_e32 v29, vcc, 0, v23, vcc
	v_add_co_u32_e32 v22, vcc, s2, v22
	global_load_dwordx4 v[170:173], v[28:29], off
	s_nop 0
	v_addc_co_u32_e32 v23, vcc, 0, v23, vcc
	global_load_dwordx4 v[174:177], v[22:23], off
	v_or_b32_e32 v22, v24, v178
	v_or_b32_e32 v7, s6, v203
	v_or3_b32 v24, v22, v2, v6
	v_or_b32_e32 v22, v30, v178
	v_mul_lo_u32 v49, v7, s48
	v_or3_b32 v30, v22, v2, v6
	v_or_b32_e32 v22, v26, v178
	v_lshlrev_b32_e32 v7, 4, v181
	v_add_u32_e32 v11, s94, v41
	v_add_u32_e32 v18, s94, v48
	v_add_u32_e32 v19, s94, v49
	v_or_b32_e32 v44, v44, v10
	v_or3_b32 v26, v22, v2, v6
	v_mov_b32_e32 v2, 0
	v_lshl_add_u64 v[184:185], s[74:75], 0, v[44:45]
	v_lshl_add_u64 v[186:187], v[8:9], 0, v[24:25]
	v_lshl_add_u64 v[188:189], v[8:9], 0, v[30:31]
	v_lshl_add_u64 v[190:191], v[8:9], 0, v[26:27]
	v_add_u32_e32 v178, v11, v3
	v_add_u32_e32 v204, v18, v10
	v_add_u32_e32 v205, v19, v7
	v_add_u32_e32 v206, v40, v7
	v_mov_b32_e32 v3, v2
	v_mov_b32_e32 v4, v2
	v_mov_b32_e32 v5, v2
	v_mov_b32_e32 v6, v2
	v_mov_b32_e32 v7, v2
	v_mov_b32_e32 v8, v2
	v_mov_b32_e32 v9, v2
	v_mov_b32_e32 v10, v2
	v_mov_b32_e32 v11, v2
	v_mov_b32_e32 v12, v2
	v_mov_b32_e32 v13, v2
	v_mov_b32_e32 v14, v2
	v_mov_b32_e32 v15, v2
	v_mov_b32_e32 v16, v2
	v_mov_b32_e32 v17, v2
	v_mov_b32_e32 v18, v2
	v_mov_b32_e32 v19, v2
	v_mov_b32_e32 v20, v2
	v_mov_b32_e32 v21, v2
	v_mov_b32_e32 v22, v2
	v_mov_b32_e32 v23, v2
	v_mov_b32_e32 v24, v2
	v_mov_b32_e32 v25, v2
	v_mov_b32_e32 v26, v2
	v_mov_b32_e32 v27, v2
	v_mov_b32_e32 v28, v2
	v_mov_b32_e32 v29, v2
	v_mov_b32_e32 v30, v2
	v_mov_b32_e32 v31, v2
	v_mov_b32_e32 v32, v2
	v_mov_b32_e32 v33, v2
	v_mov_b32_e32 v34, v2
	v_mov_b32_e32 v35, v2
	v_mov_b32_e32 v36, v2
	v_mov_b32_e32 v37, v2
	v_mov_b32_e32 v38, v2
	v_mov_b32_e32 v39, v2
	v_mov_b32_e32 v40, v2
	v_mov_b32_e32 v41, v2
	v_mov_b32_e32 v42, v2
	v_mov_b32_e32 v43, v2
	v_mov_b32_e32 v44, v2
	v_mov_b32_e32 v45, v2
	v_mov_b32_e32 v46, v2
	v_mov_b32_e32 v47, v2
	v_mov_b32_e32 v48, v2
	v_mov_b32_e32 v49, v2
	v_mov_b32_e32 v50, v2
	v_mov_b32_e32 v51, v2
	v_mov_b32_e32 v52, v2
	v_mov_b32_e32 v53, v2
	v_mov_b32_e32 v54, v2
	v_mov_b32_e32 v55, v2
	v_mov_b32_e32 v56, v2
	v_mov_b32_e32 v57, v2
	v_mov_b32_e32 v58, v2
	v_mov_b32_e32 v59, v2
	v_mov_b32_e32 v60, v2
	v_mov_b32_e32 v61, v2
	v_mov_b32_e32 v62, v2
	v_mov_b32_e32 v63, v2
	v_mov_b32_e32 v64, v2
	v_mov_b32_e32 v65, v2
	v_mov_b32_e32 v66, v2
	v_mov_b32_e32 v67, v2
	v_mov_b32_e32 v68, v2
	v_mov_b32_e32 v69, v2
	v_mov_b32_e32 v70, v2
	v_mov_b32_e32 v71, v2
	v_mov_b32_e32 v72, v2
	v_mov_b32_e32 v73, v2
	v_mov_b32_e32 v74, v2
	v_mov_b32_e32 v75, v2
	v_mov_b32_e32 v76, v2
	v_mov_b32_e32 v77, v2
	v_mov_b32_e32 v78, v2
	v_mov_b32_e32 v79, v2
	v_mov_b32_e32 v80, v2
	v_mov_b32_e32 v81, v2
	v_mov_b32_e32 v82, v2
	v_mov_b32_e32 v83, v2
	v_mov_b32_e32 v84, v2
	v_mov_b32_e32 v85, v2
	v_mov_b32_e32 v86, v2
	v_mov_b32_e32 v87, v2
	v_mov_b32_e32 v88, v2
	v_mov_b32_e32 v89, v2
	v_mov_b32_e32 v90, v2
	v_mov_b32_e32 v91, v2
	v_mov_b32_e32 v92, v2
	v_mov_b32_e32 v93, v2
	v_mov_b32_e32 v94, v2
	v_mov_b32_e32 v95, v2
	v_mov_b32_e32 v96, v2
	v_mov_b32_e32 v97, v2
	v_mov_b32_e32 v98, v2
	v_mov_b32_e32 v99, v2
	v_mov_b32_e32 v100, v2
	v_mov_b32_e32 v101, v2
	v_mov_b32_e32 v102, v2
	v_mov_b32_e32 v103, v2
	v_mov_b32_e32 v104, v2
	v_mov_b32_e32 v105, v2
	v_mov_b32_e32 v106, v2
	v_mov_b32_e32 v107, v2
	v_mov_b32_e32 v108, v2
	v_mov_b32_e32 v109, v2
	v_mov_b32_e32 v110, v2
	v_mov_b32_e32 v111, v2
	v_mov_b32_e32 v112, v2
	v_mov_b32_e32 v113, v2
	v_mov_b32_e32 v114, v2
	v_mov_b32_e32 v115, v2
	v_mov_b32_e32 v116, v2
	v_mov_b32_e32 v117, v2
	v_mov_b32_e32 v118, v2
	v_mov_b32_e32 v119, v2
	v_mov_b32_e32 v120, v2
	v_mov_b32_e32 v121, v2
	v_mov_b32_e32 v122, v2
	v_mov_b32_e32 v123, v2
	v_mov_b32_e32 v124, v2
	v_mov_b32_e32 v125, v2
	v_mov_b32_e32 v126, v2
	v_mov_b32_e32 v127, v2
	v_mov_b32_e32 v128, v2
	v_mov_b32_e32 v129, v2
	global_load_dwordx4 v[220:223], v[200:201], off nt
	s_nop 0
	global_load_dwordx4 v[224:227], v[198:199], off nt
	s_nop 0
	global_load_dwordx4 v[230:233], v[196:197], off nt
	s_nop 0
	global_load_dwordx4 v[234:237], v[194:195], off nt
	s_nop 0
	global_load_dwordx4 v[238:241], v[192:193], off nt
	s_nop 0
	global_load_dwordx4 v[242:245], v[190:191], off nt
	s_nop 0
	global_load_dwordx4 v[246:249], v[188:189], off nt
	s_nop 0
	global_load_dwordx4 v[250:253], v[186:187], off nt
	s_nop 0
	s_branch .LBB0_4201
